# nt (streaming) cache policy on the once-read weight transposes loads/stores (phase 0 and deferred chunk)
# speedup vs baseline: 1.0038x; 1.0038x over previous
.LBB0_74:
	v_ashrrev_i32_e32 v65, 3, v32
	v_lshlrev_b32_e32 v0, 2, v32
	v_add_u32_e32 v76, 64, v65
	v_add_u32_e32 v77, 0x80, v65
	v_add_u32_e32 v78, 0xc0, v65
	v_add_u32_e32 v79, 0x100, v65
	v_add_u32_e32 v80, 0x140, v65
	v_add_u32_e32 v81, 0x180, v65
	v_add_u32_e32 v82, 0x1c0, v65
	v_and_b32_e32 v64, 28, v0
	v_add_u32_e32 v0, s4, v65
	v_add_u32_e32 v2, s4, v76
	v_add_u32_e32 v8, s4, v77
	v_add_u32_e32 v10, s4, v78
	v_add_u32_e32 v16, s4, v79
	v_add_u32_e32 v18, s4, v80
	v_add_u32_e32 v24, s4, v81
	v_add_u32_e32 v26, s4, v82
	v_mad_i64_i32 v[0:1], s[2:3], s10, v0, 0
	v_mad_i64_i32 v[2:3], s[2:3], s10, v2, 0
	v_mad_i64_i32 v[8:9], s[2:3], s10, v8, 0
	v_mad_i64_i32 v[10:11], s[2:3], s10, v10, 0
	v_mad_i64_i32 v[16:17], s[2:3], s10, v16, 0
	v_mad_i64_i32 v[18:19], s[2:3], s10, v18, 0
	v_mad_i64_i32 v[24:25], s[2:3], s10, v24, 0
	v_mad_i64_i32 v[26:27], s[2:3], s10, v26, 0
	v_mov_b32_e32 v67, 0
	v_lshl_add_u64 v[0:1], v[0:1], 2, s[6:7]
	v_lshlrev_b32_e32 v66, 2, v64
	v_lshl_add_u64 v[2:3], v[2:3], 2, s[6:7]
	v_lshl_add_u64 v[8:9], v[8:9], 2, s[6:7]
	v_lshl_add_u64 v[10:11], v[10:11], 2, s[6:7]
	v_lshl_add_u64 v[16:17], v[16:17], 2, s[6:7]
	v_lshl_add_u64 v[18:19], v[18:19], 2, s[6:7]
	v_lshl_add_u64 v[24:25], v[24:25], 2, s[6:7]
	v_lshl_add_u64 v[26:27], v[26:27], 2, s[6:7]
	v_lshl_add_u64 v[0:1], v[0:1], 0, v[66:67]
	v_lshl_add_u64 v[4:5], v[2:3], 0, v[66:67]
	v_lshl_add_u64 v[8:9], v[8:9], 0, v[66:67]
	v_lshl_add_u64 v[12:13], v[10:11], 0, v[66:67]
	v_lshl_add_u64 v[16:17], v[16:17], 0, v[66:67]
	v_lshl_add_u64 v[20:21], v[18:19], 0, v[66:67]
	v_lshl_add_u64 v[24:25], v[24:25], 0, v[66:67]
	v_lshl_add_u64 v[28:29], v[26:27], 0, v[66:67]
	global_load_dwordx4 v[0:3], v[0:1], off nt
	s_nop 0
	global_load_dwordx4 v[4:7], v[4:5], off nt
	s_nop 0
	global_load_dwordx4 v[8:11], v[8:9], off nt
	s_nop 0
	global_load_dwordx4 v[12:15], v[12:13], off nt
	s_nop 0
	global_load_dwordx4 v[16:19], v[16:17], off nt
	s_nop 0
	global_load_dwordx4 v[20:23], v[20:21], off nt
	s_nop 0
	global_load_dwordx4 v[24:27], v[24:25], off nt
	s_nop 0
	global_load_dwordx4 v[28:31], v[28:29], off nt
	v_and_b32_e32 v33, 7, v32
	v_lshlrev_b32_e32 v34, 3, v33
	v_and_b32_e32 v35, 7, v65
	s_movk_i32 s2, 0x1040
	v_bitop3_b32 v37, v65, v34, -8 bitop3:0x6c
	v_mad_u32_u24 v33, v33, s2, 0
	v_and_b32_e32 v36, -8, v65
	v_or_b32_e32 v37, v37, v35
	v_lshl_add_u32 v83, v37, 1, v33
	v_add_u32_e32 v37, 64, v36
	v_xor_b32_e32 v37, v37, v34
	v_or_b32_e32 v37, v37, v35
	v_lshl_add_u32 v84, v37, 1, v33
	v_add_u32_e32 v37, 0x80, v36
	v_xor_b32_e32 v37, v37, v34
	v_or_b32_e32 v37, v37, v35
	v_lshl_add_u32 v85, v37, 1, v33
	v_add_u32_e32 v37, 0xc0, v36
	v_xor_b32_e32 v37, v37, v34
	v_or_b32_e32 v37, v37, v35
	v_lshl_add_u32 v86, v37, 1, v33
	v_add_u32_e32 v37, 0x100, v36
	v_xor_b32_e32 v37, v37, v34
	v_or_b32_e32 v37, v37, v35
	v_lshl_add_u32 v87, v37, 1, v33
	v_add_u32_e32 v37, 0x140, v36
	v_xor_b32_e32 v37, v37, v34
	v_or_b32_e32 v37, v37, v35
	v_lshl_add_u32 v88, v37, 1, v33
	v_add_u32_e32 v37, 0x180, v36
	v_add_u32_e32 v36, 0x1c0, v36
	v_xor_b32_e32 v37, v37, v34
	v_xor_b32_e32 v34, v36, v34
	v_or_b32_e32 v37, v37, v35
	v_or_b32_e32 v34, v34, v35
	v_ashrrev_i32_e32 v35, 8, v32
	v_ashrrev_i32_e32 v36, 6, v32
	v_bitop3_b32 v35, v35, v32, 63 bitop3:0x78
	v_lshl_add_u32 v89, v37, 1, v33
	v_lshl_add_u32 v90, v34, 1, v33
	v_and_b32_e32 v33, 63, v32
	s_movk_i32 s2, 0x410
	v_lshlrev_b32_e32 v38, 4, v35
	v_ashrrev_i32_e32 v37, 31, v36
	v_add_u32_e32 v35, 0x200, v32
	v_lshlrev_b32_e32 v34, 3, v33
	v_mul_lo_u32 v33, v36, s2
	v_lshlrev_b64 v[68:69], 13, v[36:37]
	v_ashrrev_i32_e32 v36, 6, v35
	v_ashrrev_i32_e32 v35, 8, v35
	v_mul_lo_u32 v37, v36, s2
	v_bitop3_b32 v35, v35, v32, 63 bitop3:0x78
	v_add_u32_e32 v39, 0, v37
	v_lshlrev_b32_e32 v40, 4, v35
	v_ashrrev_i32_e32 v37, 31, v36
	v_add_u32_e32 v35, 0x400, v32
	v_lshlrev_b64 v[70:71], 13, v[36:37]
	v_ashrrev_i32_e32 v36, 6, v35
	v_ashrrev_i32_e32 v35, 8, v35
	v_bitop3_b32 v35, v35, v32, 63 bitop3:0x78
	v_lshlrev_b32_e32 v42, 4, v35
	v_add_u32_e32 v35, 0x600, v32
	v_mul_lo_u32 v37, v36, s2
	v_lshlrev_b32_e32 v66, 1, v34
	v_ashrrev_i32_e32 v34, 6, v35
	v_ashrrev_i32_e32 v35, 8, v35
	v_add_u32_e32 v41, 0, v37
	v_ashrrev_i32_e32 v37, 31, v36
	v_bitop3_b32 v32, v35, v32, 63 bitop3:0x78
	v_mul_lo_u32 v35, v34, s2
	s_lshl_b32 s2, s86, 2
	v_add_u32_e32 v33, 0, v33
	v_lshlrev_b64 v[72:73], 13, v[36:37]
	v_add_u32_e32 v36, 0, v35
	v_lshlrev_b32_e32 v32, 4, v32
	v_ashrrev_i32_e32 v35, 31, v34
	s_add_i32 s68, s2, 0xffffafc0
	s_lshl_b32 s2, s86, 5
	s_mov_b32 s3, 0
	v_lshlrev_b64 v[74:75], 13, v[34:35]
	s_lshl_b32 s33, s84, 1
	s_lshl_b32 s87, s84, 3
	s_lshl_b32 s88, s84, 6
	s_add_i32 s69, s2, 0xfffd7e00
	s_lshl_b32 s89, s84, 2
	s_lshl_b32 s92, s84, 5
	v_add_u32_e32 v91, v33, v38
	v_add_u32_e32 v92, v39, v40
	v_add_u32_e32 v93, v41, v42
	v_add_u32_e32 v94, v36, v32
	s_mov_b64 s[6:7], s[0:1]
	s_mov_b32 s8, s4
	s_mov_b32 s71, s86
	s_branch .LBB0_79

.LBB0_76:
	v_add_u32_e32 v0, s4, v65
	v_add_u32_e32 v2, s4, v76
	v_add_u32_e32 v8, s4, v77
	v_add_u32_e32 v10, s4, v78
	v_add_u32_e32 v16, s4, v79
	v_add_u32_e32 v18, s4, v80
	v_add_u32_e32 v26, s4, v81
	v_add_u32_e32 v28, s4, v82
	v_mad_i64_i32 v[0:1], s[10:11], s20, v0, 0
	v_mad_i64_i32 v[2:3], s[10:11], s20, v2, 0
	v_mad_i64_i32 v[8:9], s[10:11], s20, v8, 0
	v_mad_i64_i32 v[10:11], s[10:11], s20, v10, 0
	v_mad_i64_i32 v[16:17], s[10:11], s20, v16, 0
	v_mad_i64_i32 v[18:19], s[10:11], s20, v18, 0
	v_mad_i64_i32 v[26:27], s[10:11], s20, v26, 0
	v_mad_i64_i32 v[28:29], s[10:11], s20, v28, 0
	v_lshl_add_u64 v[0:1], v[0:1], 2, s[14:15]
	v_lshlrev_b32_e32 v24, 2, v64
	v_mov_b32_e32 v25, v67
	v_lshl_add_u64 v[2:3], v[2:3], 2, s[14:15]
	v_lshl_add_u64 v[8:9], v[8:9], 2, s[14:15]
	v_lshl_add_u64 v[10:11], v[10:11], 2, s[14:15]
	v_lshl_add_u64 v[16:17], v[16:17], 2, s[14:15]
	v_lshl_add_u64 v[18:19], v[18:19], 2, s[14:15]
	v_lshl_add_u64 v[26:27], v[26:27], 2, s[14:15]
	v_lshl_add_u64 v[28:29], v[28:29], 2, s[14:15]
	v_lshl_add_u64 v[0:1], v[0:1], 0, v[24:25]
	v_lshl_add_u64 v[4:5], v[2:3], 0, v[24:25]
	v_lshl_add_u64 v[8:9], v[8:9], 0, v[24:25]
	v_lshl_add_u64 v[12:13], v[10:11], 0, v[24:25]
	v_lshl_add_u64 v[16:17], v[16:17], 0, v[24:25]
	v_lshl_add_u64 v[20:21], v[18:19], 0, v[24:25]
	v_lshl_add_u64 v[26:27], v[26:27], 0, v[24:25]
	v_lshl_add_u64 v[28:29], v[28:29], 0, v[24:25]
	global_load_dwordx4 v[0:3], v[0:1], off nt
	s_nop 0
	global_load_dwordx4 v[4:7], v[4:5], off nt
	s_nop 0
	global_load_dwordx4 v[8:11], v[8:9], off nt
	s_nop 0
	global_load_dwordx4 v[12:15], v[12:13], off nt
	s_nop 0
	global_load_dwordx4 v[16:19], v[16:17], off nt
	s_nop 0
	global_load_dwordx4 v[20:23], v[20:21], off nt
	s_nop 0
	global_load_dwordx4 v[24:27], v[26:27], off nt
	s_nop 0
	global_load_dwordx4 v[28:31], v[28:29], off nt
	s_waitcnt vmcnt(12)
	s_branch .LBB0_77

.LBB0_77:
	v_cvt_pk_bf16_f32 v95, v36, v67
	ds_write_b16 v83, v95
	v_cvt_pk_bf16_f32 v95, v37, v67
	ds_write_b16 v83, v95 offset:1040
	v_cvt_pk_bf16_f32 v95, v38, v67
	ds_write_b16 v83, v95 offset:2080
	v_cvt_pk_bf16_f32 v95, v39, v67
	ds_write_b16 v83, v95 offset:3120
	v_cvt_pk_bf16_f32 v95, v32, v67
	ds_write_b16 v84, v95
	v_cvt_pk_bf16_f32 v95, v33, v67
	ds_write_b16 v84, v95 offset:1040
	v_cvt_pk_bf16_f32 v95, v34, v67
	ds_write_b16 v84, v95 offset:2080
	v_cvt_pk_bf16_f32 v95, v35, v67
	ds_write_b16 v84, v95 offset:3120
	v_cvt_pk_bf16_f32 v95, v44, v67
	ds_write_b16 v85, v95
	v_cvt_pk_bf16_f32 v95, v45, v67
	ds_write_b16 v85, v95 offset:1040
	v_cvt_pk_bf16_f32 v95, v46, v67
	ds_write_b16 v85, v95 offset:2080
	v_cvt_pk_bf16_f32 v95, v47, v67
	ds_write_b16 v85, v95 offset:3120
	v_cvt_pk_bf16_f32 v95, v40, v67
	ds_write_b16 v86, v95
	v_cvt_pk_bf16_f32 v95, v41, v67
	ds_write_b16 v86, v95 offset:1040
	v_cvt_pk_bf16_f32 v95, v42, v67
	ds_write_b16 v86, v95 offset:2080
	v_cvt_pk_bf16_f32 v95, v43, v67
	ds_write_b16 v86, v95 offset:3120
	v_cvt_pk_bf16_f32 v95, v52, v67
	ds_write_b16 v87, v95
	v_cvt_pk_bf16_f32 v95, v53, v67
	ds_write_b16 v87, v95 offset:1040
	v_cvt_pk_bf16_f32 v95, v54, v67
	ds_write_b16 v87, v95 offset:2080
	v_cvt_pk_bf16_f32 v95, v55, v67
	ds_write_b16 v87, v95 offset:3120
	v_cvt_pk_bf16_f32 v95, v48, v67
	ds_write_b16 v88, v95
	v_cvt_pk_bf16_f32 v95, v49, v67
	ds_write_b16 v88, v95 offset:1040
	v_cvt_pk_bf16_f32 v95, v50, v67
	ds_write_b16 v88, v95 offset:2080
	v_cvt_pk_bf16_f32 v95, v51, v67
	ds_write_b16 v88, v95 offset:3120
	v_cvt_pk_bf16_f32 v95, v60, v67
	ds_write_b16 v89, v95
	v_cvt_pk_bf16_f32 v95, v61, v67
	ds_write_b16 v89, v95 offset:1040
	v_cvt_pk_bf16_f32 v95, v62, v67
	ds_write_b16 v89, v95 offset:2080
	v_cvt_pk_bf16_f32 v95, v63, v67
	ds_write_b16 v89, v95 offset:3120
	v_cvt_pk_bf16_f32 v95, v56, v67
	ds_write_b16 v90, v95
	v_cvt_pk_bf16_f32 v95, v57, v67
	ds_write_b16 v90, v95 offset:1040
	v_cvt_pk_bf16_f32 v95, v58, v67
	s_ashr_i32 s9, s8, 31
	s_add_i32 s71, s70, s84
	ds_write_b16 v90, v95 offset:2080
	v_cvt_pk_bf16_f32 v95, v59, v67
	ds_write_b16 v90, v95 offset:3120
	s_waitcnt lgkmcnt(0)
	s_barrier
	s_lshl_b64 s[10:11], s[8:9], 1
	ds_read_b128 v[96:99], v91
	s_add_u32 s10, s6, s10
	s_addc_u32 s11, s7, s11
	v_lshl_add_u64 v[100:101], s[10:11], 0, v[66:67]
	v_lshl_add_u64 v[102:103], v[100:101], 0, v[68:69]
	s_waitcnt lgkmcnt(0)
	global_store_dwordx4 v[102:103], v[96:99], off nt
	ds_read_b128 v[96:99], v92
	v_lshl_add_u64 v[102:103], v[100:101], 0, v[70:71]
	s_add_i32 s68, s68, s87
	s_add_i32 s69, s69, s88
	s_cmpk_gt_i32 s71, 0xa07
	s_waitcnt lgkmcnt(0)
	global_store_dwordx4 v[102:103], v[96:99], off nt
	ds_read_b128 v[96:99], v93
	v_lshl_add_u64 v[102:103], v[100:101], 0, v[72:73]
	v_lshl_add_u64 v[100:101], v[100:101], 0, v[74:75]
	s_cselect_b64 s[10:11], -1, 0
	s_waitcnt lgkmcnt(0)
	global_store_dwordx4 v[102:103], v[96:99], off nt
	ds_read_b128 v[96:99], v94
	s_waitcnt lgkmcnt(0)
	global_store_dwordx4 v[100:101], v[96:99], off nt
	s_waitcnt lgkmcnt(0)
	s_barrier

.LBB0_92:
	v_add_u32_e32 v32, s8, v65
	v_add_u32_e32 v34, s8, v76
	v_add_u32_e32 v40, s8, v77
	v_add_u32_e32 v42, s8, v78
	v_add_u32_e32 v48, s8, v79
	v_add_u32_e32 v50, s8, v80
	v_add_u32_e32 v58, s8, v81
	v_add_u32_e32 v60, s8, v82
	v_mad_i64_i32 v[32:33], s[12:13], s24, v32, 0
	v_mad_i64_i32 v[34:35], s[12:13], s24, v34, 0
	v_mad_i64_i32 v[40:41], s[12:13], s24, v40, 0
	v_mad_i64_i32 v[42:43], s[12:13], s24, v42, 0
	v_mad_i64_i32 v[48:49], s[12:13], s24, v48, 0
	v_mad_i64_i32 v[50:51], s[12:13], s24, v50, 0
	v_mad_i64_i32 v[58:59], s[12:13], s24, v58, 0
	v_mad_i64_i32 v[60:61], s[12:13], s24, v60, 0
	v_lshl_add_u64 v[32:33], v[32:33], 2, s[16:17]
	v_lshlrev_b32_e32 v56, 2, v64
	v_mov_b32_e32 v57, v67
	v_lshl_add_u64 v[34:35], v[34:35], 2, s[16:17]
	v_lshl_add_u64 v[40:41], v[40:41], 2, s[16:17]
	v_lshl_add_u64 v[42:43], v[42:43], 2, s[16:17]
	v_lshl_add_u64 v[48:49], v[48:49], 2, s[16:17]
	v_lshl_add_u64 v[50:51], v[50:51], 2, s[16:17]
	v_lshl_add_u64 v[58:59], v[58:59], 2, s[16:17]
	v_lshl_add_u64 v[60:61], v[60:61], 2, s[16:17]
	v_lshl_add_u64 v[32:33], v[32:33], 0, v[56:57]
	v_lshl_add_u64 v[34:35], v[34:35], 0, v[56:57]
	v_lshl_add_u64 v[40:41], v[40:41], 0, v[56:57]
	v_lshl_add_u64 v[42:43], v[42:43], 0, v[56:57]
	v_lshl_add_u64 v[48:49], v[48:49], 0, v[56:57]
	v_lshl_add_u64 v[50:51], v[50:51], 0, v[56:57]
	v_lshl_add_u64 v[58:59], v[58:59], 0, v[56:57]
	v_lshl_add_u64 v[56:57], v[60:61], 0, v[56:57]
	global_load_dwordx4 v[36:39], v[32:33], off nt
	s_nop 0
	global_load_dwordx4 v[32:35], v[34:35], off nt
	s_nop 0
	global_load_dwordx4 v[44:47], v[40:41], off nt
	s_nop 0
	global_load_dwordx4 v[40:43], v[42:43], off nt
	s_nop 0
	global_load_dwordx4 v[52:55], v[48:49], off nt
	s_nop 0
	global_load_dwordx4 v[48:51], v[50:51], off nt
	s_nop 0
	global_load_dwordx4 v[60:63], v[58:59], off nt
	s_nop 0
	global_load_dwordx4 v[56:59], v[56:57], off nt
	s_waitcnt vmcnt(8) lgkmcnt(0)
	s_branch .Lp0t_passa

.Lp0t_passa:
	v_cvt_pk_bf16_f32 v95, v0, v67
	ds_write_b16 v83, v95
	v_cvt_pk_bf16_f32 v95, v1, v67
	ds_write_b16 v83, v95 offset:1040
	v_cvt_pk_bf16_f32 v95, v2, v67
	ds_write_b16 v83, v95 offset:2080
	v_cvt_pk_bf16_f32 v95, v3, v67
	ds_write_b16 v83, v95 offset:3120
	v_cvt_pk_bf16_f32 v95, v4, v67
	ds_write_b16 v84, v95
	v_cvt_pk_bf16_f32 v95, v5, v67
	ds_write_b16 v84, v95 offset:1040
	v_cvt_pk_bf16_f32 v95, v6, v67
	ds_write_b16 v84, v95 offset:2080
	v_cvt_pk_bf16_f32 v95, v7, v67
	ds_write_b16 v84, v95 offset:3120
	v_cvt_pk_bf16_f32 v95, v8, v67
	ds_write_b16 v85, v95
	v_cvt_pk_bf16_f32 v95, v9, v67
	ds_write_b16 v85, v95 offset:1040
	v_cvt_pk_bf16_f32 v95, v10, v67
	ds_write_b16 v85, v95 offset:2080
	v_cvt_pk_bf16_f32 v95, v11, v67
	ds_write_b16 v85, v95 offset:3120
	v_cvt_pk_bf16_f32 v95, v12, v67
	ds_write_b16 v86, v95
	v_cvt_pk_bf16_f32 v95, v13, v67
	ds_write_b16 v86, v95 offset:1040
	v_cvt_pk_bf16_f32 v95, v14, v67
	ds_write_b16 v86, v95 offset:2080
	v_cvt_pk_bf16_f32 v95, v15, v67
	ds_write_b16 v86, v95 offset:3120
	v_cvt_pk_bf16_f32 v95, v16, v67
	ds_write_b16 v87, v95
	v_cvt_pk_bf16_f32 v95, v17, v67
	ds_write_b16 v87, v95 offset:1040
	v_cvt_pk_bf16_f32 v95, v18, v67
	ds_write_b16 v87, v95 offset:2080
	v_cvt_pk_bf16_f32 v95, v19, v67
	ds_write_b16 v87, v95 offset:3120
	v_cvt_pk_bf16_f32 v95, v20, v67
	ds_write_b16 v88, v95
	v_cvt_pk_bf16_f32 v95, v21, v67
	ds_write_b16 v88, v95 offset:1040
	v_cvt_pk_bf16_f32 v95, v22, v67
	ds_write_b16 v88, v95 offset:2080
	v_cvt_pk_bf16_f32 v95, v23, v67
	ds_write_b16 v88, v95 offset:3120
	v_cvt_pk_bf16_f32 v95, v24, v67
	ds_write_b16 v89, v95
	v_cvt_pk_bf16_f32 v95, v25, v67
	ds_write_b16 v89, v95 offset:1040
	v_cvt_pk_bf16_f32 v95, v26, v67
	ds_write_b16 v89, v95 offset:2080
	v_cvt_pk_bf16_f32 v95, v27, v67
	ds_write_b16 v89, v95 offset:3120
	v_cvt_pk_bf16_f32 v95, v28, v67
	ds_write_b16 v90, v95
	v_cvt_pk_bf16_f32 v95, v29, v67
	ds_write_b16 v90, v95 offset:1040
	v_cvt_pk_bf16_f32 v95, v30, v67
	s_ashr_i32 s5, s4, 31
	ds_write_b16 v90, v95 offset:2080
	v_cvt_pk_bf16_f32 v95, v31, v67
	ds_write_b16 v90, v95 offset:3120
	s_waitcnt lgkmcnt(0)
	s_barrier
	s_lshl_b64 s[12:13], s[4:5], 1
	ds_read_b128 v[96:99], v91
	s_add_u32 s12, s0, s12
	s_addc_u32 s13, s1, s13
	v_lshl_add_u64 v[100:101], s[12:13], 0, v[66:67]
	v_lshl_add_u64 v[102:103], v[100:101], 0, v[68:69]
	s_waitcnt lgkmcnt(0)
	global_store_dwordx4 v[102:103], v[96:99], off nt
	ds_read_b128 v[96:99], v92
	v_lshl_add_u64 v[102:103], v[100:101], 0, v[70:71]
	s_andn2_b64 vcc, exec, s[10:11]
	s_mov_b64 s[10:11], -1
	s_waitcnt lgkmcnt(0)
	global_store_dwordx4 v[102:103], v[96:99], off nt
	ds_read_b128 v[96:99], v93
	v_lshl_add_u64 v[102:103], v[100:101], 0, v[72:73]
	v_lshl_add_u64 v[100:101], v[100:101], 0, v[74:75]
	s_waitcnt lgkmcnt(0)
	global_store_dwordx4 v[102:103], v[96:99], off nt
	ds_read_b128 v[96:99], v94
	s_waitcnt lgkmcnt(0)
	global_store_dwordx4 v[100:101], v[96:99], off nt
	s_waitcnt lgkmcnt(0)
	s_barrier
	s_cbranch_vccnz .LBB0_78
	s_add_i32 s5, s33, s71
	s_cmpk_gt_i32 s5, 0xa07
	s_cbranch_scc1 .Lp0t_77w
	v_readlane_b32 s52, v254, 44
	v_readlane_b32 s53, v254, 45
	v_readlane_b32 s54, v254, 46
	v_readlane_b32 s55, v254, 47
	v_readlane_b32 s56, v254, 48
	v_readlane_b32 s57, v254, 49
	v_readlane_b32 s58, v254, 50
	v_readlane_b32 s59, v254, 51
	v_readlane_b32 s60, v254, 52
	v_readlane_b32 s61, v254, 53
	v_readlane_b32 s62, v254, 54
	v_readlane_b32 s63, v254, 55
	v_readlane_b32 s64, v254, 56
	v_readlane_b32 s65, v254, 57
	v_readlane_b32 s66, v254, 58
	v_readlane_b32 s67, v254, 59
	s_mov_b64 s[10:11], s[62:63]
	v_readlane_b32 s52, v254, 60
	v_readlane_b32 s53, v254, 61
	v_readlane_b32 s54, v254, 62
	v_readlane_b32 s55, v254, 63
	v_readlane_b32 s56, v253, 0
	v_readlane_b32 s57, v253, 1
	v_readlane_b32 s58, v253, 2
	v_readlane_b32 s59, v253, 3
	v_readlane_b32 s60, v253, 4
	v_readlane_b32 s61, v253, 5
	v_readlane_b32 s62, v253, 6
	v_readlane_b32 s63, v253, 7
	v_readlane_b32 s64, v253, 8
	v_readlane_b32 s65, v253, 9
	v_readlane_b32 s66, v253, 10
	v_readlane_b32 s67, v253, 11
	s_mov_b64 s[20:21], s[58:59]
	s_mov_b64 s[12:13], s[64:65]
	s_mov_b64 s[16:17], s[66:67]
	v_readlane_b32 s52, v254, 12
	v_readlane_b32 s53, v254, 13
	s_mov_b64 s[34:35], s[52:53]
	s_cmpk_gt_i32 s5, 0x140f
	s_mov_b64 s[24:25], -1
	v_readlane_b32 s54, v254, 14
	v_readlane_b32 s55, v254, 15
	v_readlane_b32 s56, v254, 16
	v_readlane_b32 s57, v254, 17
	v_readlane_b32 s58, v254, 18
	v_readlane_b32 s59, v254, 19
	v_readlane_b32 s60, v254, 20
	v_readlane_b32 s61, v254, 21
	v_readlane_b32 s62, v254, 22
	v_readlane_b32 s63, v254, 23
	v_readlane_b32 s64, v254, 24
	v_readlane_b32 s65, v254, 25
	v_readlane_b32 s66, v254, 26
	v_readlane_b32 s67, v254, 27
	s_cbranch_scc0 .LBB0_97
	s_add_i32 s0, s5, 0xffffebf0
	s_lshr_b32 s2, s0, 10
	s_add_i32 s0, s88, s69
	s_and_b32 s4, s0, 0xfe0
	s_lshl_b64 s[0:1], s[2:3], 25
	s_add_u32 s0, s34, s0
	s_addc_u32 s1, s35, s1
	s_lshl_b32 s9, s4, 13
	s_add_u32 s0, s0, s9
	s_addc_u32 s1, s1, 0
	s_lshl_b64 s[14:15], s[2:3], 26
	s_add_u32 s2, s20, s14
	s_addc_u32 s9, s21, s15
	s_lshl_b32 s4, s4, 2
	s_add_u32 s14, s2, s4
	s_addc_u32 s15, s9, 0
	s_add_i32 s2, s87, s68
	s_and_b32 s4, s2, 0xe00
	s_mov_b64 s[24:25], 0

.Ldt0_ud0:
	v_mul_u32_u24_e32 v96, s7, v93
	s_lshl_b32 s6, s7, 6
	v_add_u32_e32 v96, v96, v94
	v_add_u32_e32 v97, s6, v96
	v_add_u32_e32 v98, s6, v97
	v_add_u32_e32 v99, s6, v98
	v_add_u32_e32 v100, s6, v99
	v_add_u32_e32 v101, s6, v100
	v_add_u32_e32 v102, s6, v101
	v_add_u32_e32 v103, s6, v102
	global_load_dwordx4 v[4:7], v96, s[64:65] nt
	global_load_dwordx4 v[8:11], v97, s[64:65] nt
	global_load_dwordx4 v[12:15], v98, s[64:65] nt
	global_load_dwordx4 v[16:19], v99, s[64:65] nt
	global_load_dwordx4 v[20:23], v100, s[64:65] nt
	global_load_dwordx4 v[24:27], v101, s[64:65] nt
	global_load_dwordx4 v[28:31], v102, s[64:65] nt
	global_load_dwordx4 v[32:35], v103, s[64:65] nt
	s_mov_b32 s72, 1
	s_add_u32 s52, s52, s84
	s_cmpk_ge_u32 s52, 0x1c10
	s_cbranch_scc1 .Ldt0_procA
	s_cmpk_ge_u32 s52, 0x1410
	s_cbranch_scc1 .Ldt0_out1
	s_sub_i32 s0, s52, 0xa08
	s_mul_i32 s1, s0, 0xcc3
	s_lshr_b32 s1, s1, 20
	s_mul_i32 s2, s1, 0x141
	s_sub_u32 s2, s0, s2
	s_lshl_b32 s3, s2, 7
	s_mul_i32 s4, s1, 0x1410000
	s_add_u32 s3, s3, s4
	s_add_u32 s68, s54, s3
	s_addc_u32 s69, s55, 0
	s_mov_b32 s7, 0xa080
	s_lshl_b32 s4, s1, 10
	s_cmpk_lt_u32 s2, 0x80
	s_cbranch_scc1 .Ldt0_wlo1
	s_cmpk_eq_u32 s2, 0x80
	s_cbranch_scc1 .Ldt0_wlr1
	s_add_i32 s2, s2, -1

.Ldt0_ud1:
	v_mul_u32_u24_e32 v96, s7, v93
	s_lshl_b32 s6, s7, 6
	v_add_u32_e32 v96, v96, v94
	v_add_u32_e32 v97, s6, v96
	v_add_u32_e32 v98, s6, v97
	v_add_u32_e32 v99, s6, v98
	v_add_u32_e32 v100, s6, v99
	v_add_u32_e32 v101, s6, v100
	v_add_u32_e32 v102, s6, v101
	v_add_u32_e32 v103, s6, v102
	global_load_dwordx4 v[36:39], v96, s[68:69] nt
	global_load_dwordx4 v[40:43], v97, s[68:69] nt
	global_load_dwordx4 v[44:47], v98, s[68:69] nt
	global_load_dwordx4 v[48:51], v99, s[68:69] nt
	global_load_dwordx4 v[52:55], v100, s[68:69] nt
	global_load_dwordx4 v[56:59], v101, s[68:69] nt
	global_load_dwordx4 v[60:63], v102, s[68:69] nt
	global_load_dwordx4 v[64:67], v103, s[68:69] nt
	s_mov_b32 s73, 1
	s_add_u32 s52, s52, s84

.Ldt0_ud2:
	v_mul_u32_u24_e32 v96, s7, v93
	s_lshl_b32 s6, s7, 6
	v_add_u32_e32 v96, v96, v94
	v_add_u32_e32 v97, s6, v96
	v_add_u32_e32 v98, s6, v97
	v_add_u32_e32 v99, s6, v98
	v_add_u32_e32 v100, s6, v99
	v_add_u32_e32 v101, s6, v100
	v_add_u32_e32 v102, s6, v101
	v_add_u32_e32 v103, s6, v102
	global_load_dwordx4 v[4:7], v96, s[64:65] nt
	global_load_dwordx4 v[8:11], v97, s[64:65] nt
	global_load_dwordx4 v[12:15], v98, s[64:65] nt
	global_load_dwordx4 v[16:19], v99, s[64:65] nt
	global_load_dwordx4 v[20:23], v100, s[64:65] nt
	global_load_dwordx4 v[24:27], v101, s[64:65] nt
	global_load_dwordx4 v[28:31], v102, s[64:65] nt
	global_load_dwordx4 v[32:35], v103, s[64:65] nt
	s_mov_b32 s72, 1
	s_add_u32 s52, s52, s84
.Ldt0_nlA:
	ds_write_b32 v84, v68 offset:0
	ds_write_b32 v84, v69 offset:1040
	ds_write_b32 v84, v70 offset:128
	ds_write_b32 v84, v71 offset:1168
	ds_write_b32 v84, v72 offset:256
	ds_write_b32 v84, v73 offset:1296
	ds_write_b32 v84, v74 offset:384
	ds_write_b32 v84, v75 offset:1424
	ds_write_b32 v84, v76 offset:512
	ds_write_b32 v84, v77 offset:1552
	ds_write_b32 v84, v78 offset:640
	ds_write_b32 v84, v79 offset:1680
	ds_write_b32 v84, v80 offset:768
	ds_write_b32 v84, v81 offset:1808
	ds_write_b32 v84, v82 offset:896
	ds_write_b32 v84, v83 offset:1936
	s_waitcnt lgkmcnt(0)
	s_barrier
	ds_read_b128 v[68:71], v85 offset:0
	ds_read_b128 v[72:75], v86 offset:0
	ds_read_b128 v[76:79], v87 offset:0
	ds_read_b128 v[80:83], v88 offset:0
	s_waitcnt lgkmcnt(3)
	global_store_dwordx4 v89, v[68:71], s[70:71] nt
	s_waitcnt lgkmcnt(2)
	global_store_dwordx4 v90, v[72:75], s[70:71] nt
	s_waitcnt lgkmcnt(1)
	global_store_dwordx4 v91, v[76:79], s[70:71] nt
	s_waitcnt lgkmcnt(0)
	global_store_dwordx4 v92, v[80:83], s[70:71] nt
	s_add_u32 s53, s53, 1
	s_cmp_eq_u32 s73, 0
	s_cbranch_scc1 .Ldt0_end

.Ldt0_nlB:
	ds_write_b32 v84, v68 offset:33280
	ds_write_b32 v84, v69 offset:34320
	ds_write_b32 v84, v70 offset:33408
	ds_write_b32 v84, v71 offset:34448
	ds_write_b32 v84, v72 offset:33536
	ds_write_b32 v84, v73 offset:34576
	ds_write_b32 v84, v74 offset:33664
	ds_write_b32 v84, v75 offset:34704
	ds_write_b32 v84, v76 offset:33792
	ds_write_b32 v84, v77 offset:34832
	ds_write_b32 v84, v78 offset:33920
	ds_write_b32 v84, v79 offset:34960
	ds_write_b32 v84, v80 offset:34048
	ds_write_b32 v84, v81 offset:35088
	ds_write_b32 v84, v82 offset:34176
	ds_write_b32 v84, v83 offset:35216
	s_waitcnt lgkmcnt(0)
	s_barrier
	ds_read_b128 v[68:71], v85 offset:33280
	ds_read_b128 v[72:75], v86 offset:33280
	ds_read_b128 v[76:79], v87 offset:33280
	ds_read_b128 v[80:83], v88 offset:33280
	s_waitcnt lgkmcnt(3)
	global_store_dwordx4 v89, v[68:71], s[70:71] nt
	s_waitcnt lgkmcnt(2)
	global_store_dwordx4 v90, v[72:75], s[70:71] nt
	s_waitcnt lgkmcnt(1)
	global_store_dwordx4 v91, v[76:79], s[70:71] nt
	s_waitcnt lgkmcnt(0)
	global_store_dwordx4 v92, v[80:83], s[70:71] nt
	s_add_u32 s53, s53, 1
	s_cmp_eq_u32 s72, 0
	s_cbranch_scc0 .Ldt0_procA
